# half-1 hgrn_pass_b load ring 6 deep instead of 8
# baseline (speedup 1.0000x reference)
.Lhb1_start:
	s_cmp_lt_u32 s72, 128
	s_cbranch_scc1 .Lhb1_done
	s_waitcnt vmcnt(0) lgkmcnt(0)
	s_sub_u32 s0, s72, 128
	s_lshr_b32 s1, s0, 3
	s_and_b32 s4, s0, 7
	s_lshl_b32 s4, s4, 9
	v_add_u32_e32 v0, s4, v177
	v_lshlrev_b32_e32 v2, 4, v0
	v_lshrrev_b32_e32 v3, 5, v0
	v_lshlrev_b32_e32 v3, 2, v3
	v_readlane_b32 s38, v253, 1
	v_readlane_b32 s39, v253, 2
	v_readlane_b32 s44, v252, 6
	v_readlane_b32 s45, v252, 7
	s_lshl_b32 s5, s1, 22
	s_nop 3
	s_add_u32 s38, s38, s5
	s_addc_u32 s39, s39, 0
	s_mov_b64 s[40:41], s[38:39]
	s_lshl_b32 s5, s1, 15
	s_add_u32 s42, s2, s5
	s_addc_u32 s43, s3, 0
	s_lshr_b32 s5, s1, 3
	s_lshl_b32 s5, s5, 1
	s_and_b32 s6, s1, 1
	s_or_b32 s5, s5, s6
	s_lshl_b32 s5, s5, 2
	s_bfe_u32 s6, s1, 0x20001
	s_or_b32 s5, s5, s6
	s_lshl_b32 s5, s5, 16
	s_add_u32 s44, s44, s5
	s_addc_u32 s45, s45, 0
	global_load_dwordx4 v[4:7], v2, s[44:45]
	global_load_dwordx4 v[8:11], v2, s[38:39]
	global_load_dword v32, v3, s[42:43]
	s_add_u32 s38, s38, 0x10000
	s_addc_u32 s39, s39, 0
	s_add_u32 s42, s42, 0x200
	s_addc_u32 s43, s43, 0
	global_load_dwordx4 v[12:15], v2, s[38:39]
	global_load_dword v33, v3, s[42:43]
	s_add_u32 s38, s38, 0x10000
	s_addc_u32 s39, s39, 0
	s_add_u32 s42, s42, 0x200
	s_addc_u32 s43, s43, 0
	global_load_dwordx4 v[16:19], v2, s[38:39]
	global_load_dword v34, v3, s[42:43]
	s_add_u32 s38, s38, 0x10000
	s_addc_u32 s39, s39, 0
	s_add_u32 s42, s42, 0x200
	s_addc_u32 s43, s43, 0
	global_load_dwordx4 v[20:23], v2, s[38:39]
	global_load_dword v35, v3, s[42:43]
	s_add_u32 s38, s38, 0x10000
	s_addc_u32 s39, s39, 0
	s_add_u32 s42, s42, 0x200
	s_addc_u32 s43, s43, 0
	global_load_dwordx4 v[24:27], v2, s[38:39]
	global_load_dword v36, v3, s[42:43]
	s_add_u32 s38, s38, 0x10000
	s_addc_u32 s39, s39, 0
	s_add_u32 s42, s42, 0x200
	s_addc_u32 s43, s43, 0
	global_load_dwordx4 v[28:31], v2, s[38:39]
	global_load_dword v37, v3, s[42:43]
	s_add_u32 s38, s38, 0x10000
	s_addc_u32 s39, s39, 0
	s_add_u32 s42, s42, 0x200
	s_addc_u32 s43, s43, 0
	s_waitcnt vmcnt(10)
	global_store_dwordx4 v2, v[4:7], s[40:41]
	s_add_u32 s40, s40, 0x10000
	s_addc_u32 s41, s41, 0
	v_fma_f32 v4, v4, v32, v8
	v_fma_f32 v5, v5, v32, v9
	v_fma_f32 v6, v6, v32, v10
	v_fma_f32 v7, v7, v32, v11
	global_load_dwordx4 v[8:11], v2, s[38:39]
	global_load_dword v32, v3, s[42:43]
	s_add_u32 s38, s38, 0x10000
	s_addc_u32 s39, s39, 0
	s_add_u32 s42, s42, 0x200
	s_addc_u32 s43, s43, 0
	s_waitcnt vmcnt(11)
	global_store_dwordx4 v2, v[4:7], s[40:41]
	s_add_u32 s40, s40, 0x10000
	s_addc_u32 s41, s41, 0
	v_fma_f32 v4, v4, v33, v12
	v_fma_f32 v5, v5, v33, v13
	v_fma_f32 v6, v6, v33, v14
	v_fma_f32 v7, v7, v33, v15
	global_load_dwordx4 v[12:15], v2, s[38:39]
	global_load_dword v33, v3, s[42:43]
	s_add_u32 s38, s38, 0x10000
	s_addc_u32 s39, s39, 0
	s_add_u32 s42, s42, 0x200
	s_addc_u32 s43, s43, 0
	s_waitcnt vmcnt(12)
	global_store_dwordx4 v2, v[4:7], s[40:41]
	s_add_u32 s40, s40, 0x10000
	s_addc_u32 s41, s41, 0
	v_fma_f32 v4, v4, v34, v16
	v_fma_f32 v5, v5, v34, v17
	v_fma_f32 v6, v6, v34, v18
	v_fma_f32 v7, v7, v34, v19
	global_load_dwordx4 v[16:19], v2, s[38:39]
	global_load_dword v34, v3, s[42:43]
	s_add_u32 s38, s38, 0x10000
	s_addc_u32 s39, s39, 0
	s_add_u32 s42, s42, 0x200
	s_addc_u32 s43, s43, 0
	s_waitcnt vmcnt(13)
	global_store_dwordx4 v2, v[4:7], s[40:41]
	s_add_u32 s40, s40, 0x10000
	s_addc_u32 s41, s41, 0
	v_fma_f32 v4, v4, v35, v20
	v_fma_f32 v5, v5, v35, v21
	v_fma_f32 v6, v6, v35, v22
	v_fma_f32 v7, v7, v35, v23
	global_load_dwordx4 v[20:23], v2, s[38:39]
	global_load_dword v35, v3, s[42:43]
	s_add_u32 s38, s38, 0x10000
	s_addc_u32 s39, s39, 0
	s_add_u32 s42, s42, 0x200
	s_addc_u32 s43, s43, 0
	s_waitcnt vmcnt(14)
	global_store_dwordx4 v2, v[4:7], s[40:41]
	s_add_u32 s40, s40, 0x10000
	s_addc_u32 s41, s41, 0
	v_fma_f32 v4, v4, v36, v24
	v_fma_f32 v5, v5, v36, v25
	v_fma_f32 v6, v6, v36, v26
	v_fma_f32 v7, v7, v36, v27
	global_load_dwordx4 v[24:27], v2, s[38:39]
	global_load_dword v36, v3, s[42:43]
	s_add_u32 s38, s38, 0x10000
	s_addc_u32 s39, s39, 0
	s_add_u32 s42, s42, 0x200
	s_addc_u32 s43, s43, 0
	s_waitcnt vmcnt(15)
	global_store_dwordx4 v2, v[4:7], s[40:41]
	s_add_u32 s40, s40, 0x10000
	s_addc_u32 s41, s41, 0
	v_fma_f32 v4, v4, v37, v28
	v_fma_f32 v5, v5, v37, v29
	v_fma_f32 v6, v6, v37, v30
	v_fma_f32 v7, v7, v37, v31
	global_load_dwordx4 v[28:31], v2, s[38:39]
	global_load_dword v37, v3, s[42:43]
	s_add_u32 s38, s38, 0x10000
	s_addc_u32 s39, s39, 0
	s_add_u32 s42, s42, 0x200
	s_addc_u32 s43, s43, 0
	s_waitcnt vmcnt(15)
	global_store_dwordx4 v2, v[4:7], s[40:41]
	s_add_u32 s40, s40, 0x10000
	s_addc_u32 s41, s41, 0
	v_fma_f32 v4, v4, v32, v8
	v_fma_f32 v5, v5, v32, v9
	v_fma_f32 v6, v6, v32, v10
	v_fma_f32 v7, v7, v32, v11
	global_load_dwordx4 v[8:11], v2, s[38:39]
	global_load_dword v32, v3, s[42:43]
	s_add_u32 s38, s38, 0x10000
	s_addc_u32 s39, s39, 0
	s_add_u32 s42, s42, 0x200
	s_addc_u32 s43, s43, 0
	s_waitcnt vmcnt(15)
	global_store_dwordx4 v2, v[4:7], s[40:41]
	s_add_u32 s40, s40, 0x10000
	s_addc_u32 s41, s41, 0
	v_fma_f32 v4, v4, v33, v12
	v_fma_f32 v5, v5, v33, v13
	v_fma_f32 v6, v6, v33, v14
	v_fma_f32 v7, v7, v33, v15
	global_load_dwordx4 v[12:15], v2, s[38:39]
	global_load_dword v33, v3, s[42:43]
	s_add_u32 s38, s38, 0x10000
	s_addc_u32 s39, s39, 0
	s_add_u32 s42, s42, 0x200
	s_addc_u32 s43, s43, 0
	s_waitcnt vmcnt(15)
	global_store_dwordx4 v2, v[4:7], s[40:41]
	s_add_u32 s40, s40, 0x10000
	s_addc_u32 s41, s41, 0
	v_fma_f32 v4, v4, v34, v16
	v_fma_f32 v5, v5, v34, v17
	v_fma_f32 v6, v6, v34, v18
	v_fma_f32 v7, v7, v34, v19
	global_load_dwordx4 v[16:19], v2, s[38:39]
	global_load_dword v34, v3, s[42:43]
	s_add_u32 s38, s38, 0x10000
	s_addc_u32 s39, s39, 0
	s_add_u32 s42, s42, 0x200
	s_addc_u32 s43, s43, 0
	s_waitcnt vmcnt(15)
	global_store_dwordx4 v2, v[4:7], s[40:41]
	s_add_u32 s40, s40, 0x10000
	s_addc_u32 s41, s41, 0
	v_fma_f32 v4, v4, v35, v20
	v_fma_f32 v5, v5, v35, v21
	v_fma_f32 v6, v6, v35, v22
	v_fma_f32 v7, v7, v35, v23
	global_load_dwordx4 v[20:23], v2, s[38:39]
	global_load_dword v35, v3, s[42:43]
	s_add_u32 s38, s38, 0x10000
	s_addc_u32 s39, s39, 0
	s_add_u32 s42, s42, 0x200
	s_addc_u32 s43, s43, 0
	s_waitcnt vmcnt(15)
	global_store_dwordx4 v2, v[4:7], s[40:41]
	s_add_u32 s40, s40, 0x10000
	s_addc_u32 s41, s41, 0
	v_fma_f32 v4, v4, v36, v24
	v_fma_f32 v5, v5, v36, v25
	v_fma_f32 v6, v6, v36, v26
	v_fma_f32 v7, v7, v36, v27
	global_load_dwordx4 v[24:27], v2, s[38:39]
	global_load_dword v36, v3, s[42:43]
	s_add_u32 s38, s38, 0x10000
	s_addc_u32 s39, s39, 0
	s_add_u32 s42, s42, 0x200
	s_addc_u32 s43, s43, 0
	s_waitcnt vmcnt(15)
	global_store_dwordx4 v2, v[4:7], s[40:41]
	s_add_u32 s40, s40, 0x10000
	s_addc_u32 s41, s41, 0
	v_fma_f32 v4, v4, v37, v28
	v_fma_f32 v5, v5, v37, v29
	v_fma_f32 v6, v6, v37, v30
	v_fma_f32 v7, v7, v37, v31
	global_load_dwordx4 v[28:31], v2, s[38:39]
	global_load_dword v37, v3, s[42:43]
	s_add_u32 s38, s38, 0x10000
	s_addc_u32 s39, s39, 0
	s_add_u32 s42, s42, 0x200
	s_addc_u32 s43, s43, 0
	s_waitcnt vmcnt(15)
	global_store_dwordx4 v2, v[4:7], s[40:41]
	s_add_u32 s40, s40, 0x10000
	s_addc_u32 s41, s41, 0
	v_fma_f32 v4, v4, v32, v8
	v_fma_f32 v5, v5, v32, v9
	v_fma_f32 v6, v6, v32, v10
	v_fma_f32 v7, v7, v32, v11
	global_load_dwordx4 v[8:11], v2, s[38:39]
	global_load_dword v32, v3, s[42:43]
	s_add_u32 s38, s38, 0x10000
	s_addc_u32 s39, s39, 0
	s_add_u32 s42, s42, 0x200
	s_addc_u32 s43, s43, 0
	s_waitcnt vmcnt(15)
	global_store_dwordx4 v2, v[4:7], s[40:41]
	s_add_u32 s40, s40, 0x10000
	s_addc_u32 s41, s41, 0
	v_fma_f32 v4, v4, v33, v12
	v_fma_f32 v5, v5, v33, v13
	v_fma_f32 v6, v6, v33, v14
	v_fma_f32 v7, v7, v33, v15
	global_load_dwordx4 v[12:15], v2, s[38:39]
	global_load_dword v33, v3, s[42:43]
	s_add_u32 s38, s38, 0x10000
	s_addc_u32 s39, s39, 0
	s_add_u32 s42, s42, 0x200
	s_addc_u32 s43, s43, 0
	s_waitcnt vmcnt(15)
	global_store_dwordx4 v2, v[4:7], s[40:41]
	s_add_u32 s40, s40, 0x10000
	s_addc_u32 s41, s41, 0
	v_fma_f32 v4, v4, v34, v16
	v_fma_f32 v5, v5, v34, v17
	v_fma_f32 v6, v6, v34, v18
	v_fma_f32 v7, v7, v34, v19
	global_load_dwordx4 v[16:19], v2, s[38:39]
	global_load_dword v34, v3, s[42:43]
	s_add_u32 s38, s38, 0x10000
	s_addc_u32 s39, s39, 0
	s_add_u32 s42, s42, 0x200
	s_addc_u32 s43, s43, 0
	s_waitcnt vmcnt(15)
	global_store_dwordx4 v2, v[4:7], s[40:41]
	s_add_u32 s40, s40, 0x10000
	s_addc_u32 s41, s41, 0
	v_fma_f32 v4, v4, v35, v20
	v_fma_f32 v5, v5, v35, v21
	v_fma_f32 v6, v6, v35, v22
	v_fma_f32 v7, v7, v35, v23
	global_load_dwordx4 v[20:23], v2, s[38:39]
	global_load_dword v35, v3, s[42:43]
	s_add_u32 s38, s38, 0x10000
	s_addc_u32 s39, s39, 0
	s_add_u32 s42, s42, 0x200
	s_addc_u32 s43, s43, 0
	s_waitcnt vmcnt(15)
	global_store_dwordx4 v2, v[4:7], s[40:41]
	s_add_u32 s40, s40, 0x10000
	s_addc_u32 s41, s41, 0
	v_fma_f32 v4, v4, v36, v24
	v_fma_f32 v5, v5, v36, v25
	v_fma_f32 v6, v6, v36, v26
	v_fma_f32 v7, v7, v36, v27
	global_load_dwordx4 v[24:27], v2, s[38:39]
	global_load_dword v36, v3, s[42:43]
	s_add_u32 s38, s38, 0x10000
	s_addc_u32 s39, s39, 0
	s_add_u32 s42, s42, 0x200
	s_addc_u32 s43, s43, 0
	s_waitcnt vmcnt(15)
	global_store_dwordx4 v2, v[4:7], s[40:41]
	s_add_u32 s40, s40, 0x10000
	s_addc_u32 s41, s41, 0
	v_fma_f32 v4, v4, v37, v28
	v_fma_f32 v5, v5, v37, v29
	v_fma_f32 v6, v6, v37, v30
	v_fma_f32 v7, v7, v37, v31
	global_load_dwordx4 v[28:31], v2, s[38:39]
	global_load_dword v37, v3, s[42:43]
	s_add_u32 s38, s38, 0x10000
	s_addc_u32 s39, s39, 0
	s_add_u32 s42, s42, 0x200
	s_addc_u32 s43, s43, 0
	s_waitcnt vmcnt(15)
	global_store_dwordx4 v2, v[4:7], s[40:41]
	s_add_u32 s40, s40, 0x10000
	s_addc_u32 s41, s41, 0
	v_fma_f32 v4, v4, v32, v8
	v_fma_f32 v5, v5, v32, v9
	v_fma_f32 v6, v6, v32, v10
	v_fma_f32 v7, v7, v32, v11
	global_load_dwordx4 v[8:11], v2, s[38:39]
	global_load_dword v32, v3, s[42:43]
	s_add_u32 s38, s38, 0x10000
	s_addc_u32 s39, s39, 0
	s_add_u32 s42, s42, 0x200
	s_addc_u32 s43, s43, 0
	s_waitcnt vmcnt(15)
	global_store_dwordx4 v2, v[4:7], s[40:41]
	s_add_u32 s40, s40, 0x10000
	s_addc_u32 s41, s41, 0
	v_fma_f32 v4, v4, v33, v12
	v_fma_f32 v5, v5, v33, v13
	v_fma_f32 v6, v6, v33, v14
	v_fma_f32 v7, v7, v33, v15
	global_load_dwordx4 v[12:15], v2, s[38:39]
	global_load_dword v33, v3, s[42:43]
	s_add_u32 s38, s38, 0x10000
	s_addc_u32 s39, s39, 0
	s_add_u32 s42, s42, 0x200
	s_addc_u32 s43, s43, 0
	s_waitcnt vmcnt(15)
	global_store_dwordx4 v2, v[4:7], s[40:41]
	s_add_u32 s40, s40, 0x10000
	s_addc_u32 s41, s41, 0
	v_fma_f32 v4, v4, v34, v16
	v_fma_f32 v5, v5, v34, v17
	v_fma_f32 v6, v6, v34, v18
	v_fma_f32 v7, v7, v34, v19
	global_load_dwordx4 v[16:19], v2, s[38:39]
	global_load_dword v34, v3, s[42:43]
	s_add_u32 s38, s38, 0x10000
	s_addc_u32 s39, s39, 0
	s_add_u32 s42, s42, 0x200
	s_addc_u32 s43, s43, 0
	s_waitcnt vmcnt(15)
	global_store_dwordx4 v2, v[4:7], s[40:41]
	s_add_u32 s40, s40, 0x10000
	s_addc_u32 s41, s41, 0
	v_fma_f32 v4, v4, v35, v20
	v_fma_f32 v5, v5, v35, v21
	v_fma_f32 v6, v6, v35, v22
	v_fma_f32 v7, v7, v35, v23
	global_load_dwordx4 v[20:23], v2, s[38:39]
	global_load_dword v35, v3, s[42:43]
	s_add_u32 s38, s38, 0x10000
	s_addc_u32 s39, s39, 0
	s_add_u32 s42, s42, 0x200
	s_addc_u32 s43, s43, 0
	s_waitcnt vmcnt(15)
	global_store_dwordx4 v2, v[4:7], s[40:41]
	s_add_u32 s40, s40, 0x10000
	s_addc_u32 s41, s41, 0
	v_fma_f32 v4, v4, v36, v24
	v_fma_f32 v5, v5, v36, v25
	v_fma_f32 v6, v6, v36, v26
	v_fma_f32 v7, v7, v36, v27
	global_load_dwordx4 v[24:27], v2, s[38:39]
	global_load_dword v36, v3, s[42:43]
	s_add_u32 s38, s38, 0x10000
	s_addc_u32 s39, s39, 0
	s_add_u32 s42, s42, 0x200
	s_addc_u32 s43, s43, 0
	s_waitcnt vmcnt(15)
	global_store_dwordx4 v2, v[4:7], s[40:41]
	s_add_u32 s40, s40, 0x10000
	s_addc_u32 s41, s41, 0
	v_fma_f32 v4, v4, v37, v28
	v_fma_f32 v5, v5, v37, v29
	v_fma_f32 v6, v6, v37, v30
	v_fma_f32 v7, v7, v37, v31
	global_load_dwordx4 v[28:31], v2, s[38:39]
	global_load_dword v37, v3, s[42:43]
	s_add_u32 s38, s38, 0x10000
	s_addc_u32 s39, s39, 0
	s_add_u32 s42, s42, 0x200
	s_addc_u32 s43, s43, 0
	s_waitcnt vmcnt(15)
	global_store_dwordx4 v2, v[4:7], s[40:41]
	s_add_u32 s40, s40, 0x10000
	s_addc_u32 s41, s41, 0
	v_fma_f32 v4, v4, v32, v8
	v_fma_f32 v5, v5, v32, v9
	v_fma_f32 v6, v6, v32, v10
	v_fma_f32 v7, v7, v32, v11
	global_load_dwordx4 v[8:11], v2, s[38:39]
	global_load_dword v32, v3, s[42:43]
	s_add_u32 s38, s38, 0x10000
	s_addc_u32 s39, s39, 0
	s_add_u32 s42, s42, 0x200
	s_addc_u32 s43, s43, 0
	s_waitcnt vmcnt(15)
	global_store_dwordx4 v2, v[4:7], s[40:41]
	s_add_u32 s40, s40, 0x10000
	s_addc_u32 s41, s41, 0
	v_fma_f32 v4, v4, v33, v12
	v_fma_f32 v5, v5, v33, v13
	v_fma_f32 v6, v6, v33, v14
	v_fma_f32 v7, v7, v33, v15
	global_load_dwordx4 v[12:15], v2, s[38:39]
	global_load_dword v33, v3, s[42:43]
	s_add_u32 s38, s38, 0x10000
	s_addc_u32 s39, s39, 0
	s_add_u32 s42, s42, 0x200
	s_addc_u32 s43, s43, 0
	s_waitcnt vmcnt(15)
	global_store_dwordx4 v2, v[4:7], s[40:41]
	s_add_u32 s40, s40, 0x10000
	s_addc_u32 s41, s41, 0
	v_fma_f32 v4, v4, v34, v16
	v_fma_f32 v5, v5, v34, v17
	v_fma_f32 v6, v6, v34, v18
	v_fma_f32 v7, v7, v34, v19
	global_load_dwordx4 v[16:19], v2, s[38:39]
	global_load_dword v34, v3, s[42:43]
	s_add_u32 s38, s38, 0x10000
	s_addc_u32 s39, s39, 0
	s_add_u32 s42, s42, 0x200
	s_addc_u32 s43, s43, 0
	s_waitcnt vmcnt(15)
	global_store_dwordx4 v2, v[4:7], s[40:41]
	s_add_u32 s40, s40, 0x10000
	s_addc_u32 s41, s41, 0
	v_fma_f32 v4, v4, v35, v20
	v_fma_f32 v5, v5, v35, v21
	v_fma_f32 v6, v6, v35, v22
	v_fma_f32 v7, v7, v35, v23
	global_load_dwordx4 v[20:23], v2, s[38:39]
	global_load_dword v35, v3, s[42:43]
	s_add_u32 s38, s38, 0x10000
	s_addc_u32 s39, s39, 0
	s_add_u32 s42, s42, 0x200
	s_addc_u32 s43, s43, 0
	s_waitcnt vmcnt(15)
	global_store_dwordx4 v2, v[4:7], s[40:41]
	s_add_u32 s40, s40, 0x10000
	s_addc_u32 s41, s41, 0
	v_fma_f32 v4, v4, v36, v24
	v_fma_f32 v5, v5, v36, v25
	v_fma_f32 v6, v6, v36, v26
	v_fma_f32 v7, v7, v36, v27
	global_load_dwordx4 v[24:27], v2, s[38:39]
	global_load_dword v36, v3, s[42:43]
	s_add_u32 s38, s38, 0x10000
	s_addc_u32 s39, s39, 0
	s_add_u32 s42, s42, 0x200
	s_addc_u32 s43, s43, 0
	s_waitcnt vmcnt(15)
	global_store_dwordx4 v2, v[4:7], s[40:41]
	s_add_u32 s40, s40, 0x10000
	s_addc_u32 s41, s41, 0
	v_fma_f32 v4, v4, v37, v28
	v_fma_f32 v5, v5, v37, v29
	v_fma_f32 v6, v6, v37, v30
	v_fma_f32 v7, v7, v37, v31
	global_load_dwordx4 v[28:31], v2, s[38:39]
	global_load_dword v37, v3, s[42:43]
	s_add_u32 s38, s38, 0x10000
	s_addc_u32 s39, s39, 0
	s_add_u32 s42, s42, 0x200
	s_addc_u32 s43, s43, 0
	s_waitcnt vmcnt(15)
	global_store_dwordx4 v2, v[4:7], s[40:41]
	s_add_u32 s40, s40, 0x10000
	s_addc_u32 s41, s41, 0
	v_fma_f32 v4, v4, v32, v8
	v_fma_f32 v5, v5, v32, v9
	v_fma_f32 v6, v6, v32, v10
	v_fma_f32 v7, v7, v32, v11
	global_load_dwordx4 v[8:11], v2, s[38:39]
	global_load_dword v32, v3, s[42:43]
	s_add_u32 s38, s38, 0x10000
	s_addc_u32 s39, s39, 0
	s_add_u32 s42, s42, 0x200
	s_addc_u32 s43, s43, 0
	s_waitcnt vmcnt(15)
	global_store_dwordx4 v2, v[4:7], s[40:41]
	s_add_u32 s40, s40, 0x10000
	s_addc_u32 s41, s41, 0
	v_fma_f32 v4, v4, v33, v12
	v_fma_f32 v5, v5, v33, v13
	v_fma_f32 v6, v6, v33, v14
	v_fma_f32 v7, v7, v33, v15
	global_load_dwordx4 v[12:15], v2, s[38:39]
	global_load_dword v33, v3, s[42:43]
	s_add_u32 s38, s38, 0x10000
	s_addc_u32 s39, s39, 0
	s_add_u32 s42, s42, 0x200
	s_addc_u32 s43, s43, 0
	s_waitcnt vmcnt(15)
	global_store_dwordx4 v2, v[4:7], s[40:41]
	s_add_u32 s40, s40, 0x10000
	s_addc_u32 s41, s41, 0
	v_fma_f32 v4, v4, v34, v16
	v_fma_f32 v5, v5, v34, v17
	v_fma_f32 v6, v6, v34, v18
	v_fma_f32 v7, v7, v34, v19
	global_load_dwordx4 v[16:19], v2, s[38:39]
	global_load_dword v34, v3, s[42:43]
	s_add_u32 s38, s38, 0x10000
	s_addc_u32 s39, s39, 0
	s_add_u32 s42, s42, 0x200
	s_addc_u32 s43, s43, 0
	s_waitcnt vmcnt(15)
	global_store_dwordx4 v2, v[4:7], s[40:41]
	s_add_u32 s40, s40, 0x10000
	s_addc_u32 s41, s41, 0
	v_fma_f32 v4, v4, v35, v20
	v_fma_f32 v5, v5, v35, v21
	v_fma_f32 v6, v6, v35, v22
	v_fma_f32 v7, v7, v35, v23
	global_load_dwordx4 v[20:23], v2, s[38:39]
	global_load_dword v35, v3, s[42:43]
	s_add_u32 s38, s38, 0x10000
	s_addc_u32 s39, s39, 0
	s_add_u32 s42, s42, 0x200
	s_addc_u32 s43, s43, 0
	s_waitcnt vmcnt(15)
	global_store_dwordx4 v2, v[4:7], s[40:41]
	s_add_u32 s40, s40, 0x10000
	s_addc_u32 s41, s41, 0
	v_fma_f32 v4, v4, v36, v24
	v_fma_f32 v5, v5, v36, v25
	v_fma_f32 v6, v6, v36, v26
	v_fma_f32 v7, v7, v36, v27
	global_load_dwordx4 v[24:27], v2, s[38:39]
	global_load_dword v36, v3, s[42:43]
	s_add_u32 s38, s38, 0x10000
	s_addc_u32 s39, s39, 0
	s_add_u32 s42, s42, 0x200
	s_addc_u32 s43, s43, 0
	s_waitcnt vmcnt(15)
	global_store_dwordx4 v2, v[4:7], s[40:41]
	s_add_u32 s40, s40, 0x10000
	s_addc_u32 s41, s41, 0
	v_fma_f32 v4, v4, v37, v28
	v_fma_f32 v5, v5, v37, v29
	v_fma_f32 v6, v6, v37, v30
	v_fma_f32 v7, v7, v37, v31
	global_load_dwordx4 v[28:31], v2, s[38:39]
	global_load_dword v37, v3, s[42:43]
	s_add_u32 s38, s38, 0x10000
	s_addc_u32 s39, s39, 0
	s_add_u32 s42, s42, 0x200
	s_addc_u32 s43, s43, 0
	s_waitcnt vmcnt(15)
	global_store_dwordx4 v2, v[4:7], s[40:41]
	s_add_u32 s40, s40, 0x10000
	s_addc_u32 s41, s41, 0
	v_fma_f32 v4, v4, v32, v8
	v_fma_f32 v5, v5, v32, v9
	v_fma_f32 v6, v6, v32, v10
	v_fma_f32 v7, v7, v32, v11
	global_load_dwordx4 v[8:11], v2, s[38:39]
	global_load_dword v32, v3, s[42:43]
	s_add_u32 s38, s38, 0x10000
	s_addc_u32 s39, s39, 0
	s_add_u32 s42, s42, 0x200
	s_addc_u32 s43, s43, 0
	s_waitcnt vmcnt(15)
	global_store_dwordx4 v2, v[4:7], s[40:41]
	s_add_u32 s40, s40, 0x10000
	s_addc_u32 s41, s41, 0
	v_fma_f32 v4, v4, v33, v12
	v_fma_f32 v5, v5, v33, v13
	v_fma_f32 v6, v6, v33, v14
	v_fma_f32 v7, v7, v33, v15
	global_load_dwordx4 v[12:15], v2, s[38:39]
	global_load_dword v33, v3, s[42:43]
	s_add_u32 s38, s38, 0x10000
	s_addc_u32 s39, s39, 0
	s_add_u32 s42, s42, 0x200
	s_addc_u32 s43, s43, 0
	s_waitcnt vmcnt(15)
	global_store_dwordx4 v2, v[4:7], s[40:41]
	s_add_u32 s40, s40, 0x10000
	s_addc_u32 s41, s41, 0
	v_fma_f32 v4, v4, v34, v16
	v_fma_f32 v5, v5, v34, v17
	v_fma_f32 v6, v6, v34, v18
	v_fma_f32 v7, v7, v34, v19
	global_load_dwordx4 v[16:19], v2, s[38:39]
	global_load_dword v34, v3, s[42:43]
	s_add_u32 s38, s38, 0x10000
	s_addc_u32 s39, s39, 0
	s_add_u32 s42, s42, 0x200
	s_addc_u32 s43, s43, 0
	s_waitcnt vmcnt(15)
	global_store_dwordx4 v2, v[4:7], s[40:41]
	s_add_u32 s40, s40, 0x10000
	s_addc_u32 s41, s41, 0
	v_fma_f32 v4, v4, v35, v20
	v_fma_f32 v5, v5, v35, v21
	v_fma_f32 v6, v6, v35, v22
	v_fma_f32 v7, v7, v35, v23
	global_load_dwordx4 v[20:23], v2, s[38:39]
	global_load_dword v35, v3, s[42:43]
	s_add_u32 s38, s38, 0x10000
	s_addc_u32 s39, s39, 0
	s_add_u32 s42, s42, 0x200
	s_addc_u32 s43, s43, 0
	s_waitcnt vmcnt(15)
	global_store_dwordx4 v2, v[4:7], s[40:41]
	s_add_u32 s40, s40, 0x10000
	s_addc_u32 s41, s41, 0
	v_fma_f32 v4, v4, v36, v24
	v_fma_f32 v5, v5, v36, v25
	v_fma_f32 v6, v6, v36, v26
	v_fma_f32 v7, v7, v36, v27
	global_load_dwordx4 v[24:27], v2, s[38:39]
	global_load_dword v36, v3, s[42:43]
	s_add_u32 s38, s38, 0x10000
	s_addc_u32 s39, s39, 0
	s_add_u32 s42, s42, 0x200
	s_addc_u32 s43, s43, 0
	s_waitcnt vmcnt(15)
	global_store_dwordx4 v2, v[4:7], s[40:41]
	s_add_u32 s40, s40, 0x10000
	s_addc_u32 s41, s41, 0
	v_fma_f32 v4, v4, v37, v28
	v_fma_f32 v5, v5, v37, v29
	v_fma_f32 v6, v6, v37, v30
	v_fma_f32 v7, v7, v37, v31
	global_load_dwordx4 v[28:31], v2, s[38:39]
	global_load_dword v37, v3, s[42:43]
	s_add_u32 s38, s38, 0x10000
	s_addc_u32 s39, s39, 0
	s_add_u32 s42, s42, 0x200
	s_addc_u32 s43, s43, 0
	s_waitcnt vmcnt(15)
	global_store_dwordx4 v2, v[4:7], s[40:41]
	s_add_u32 s40, s40, 0x10000
	s_addc_u32 s41, s41, 0
	v_fma_f32 v4, v4, v32, v8
	v_fma_f32 v5, v5, v32, v9
	v_fma_f32 v6, v6, v32, v10
	v_fma_f32 v7, v7, v32, v11
	global_load_dwordx4 v[8:11], v2, s[38:39]
	global_load_dword v32, v3, s[42:43]
	s_add_u32 s38, s38, 0x10000
	s_addc_u32 s39, s39, 0
	s_add_u32 s42, s42, 0x200
	s_addc_u32 s43, s43, 0
	s_waitcnt vmcnt(15)
	global_store_dwordx4 v2, v[4:7], s[40:41]
	s_add_u32 s40, s40, 0x10000
	s_addc_u32 s41, s41, 0
	v_fma_f32 v4, v4, v33, v12
	v_fma_f32 v5, v5, v33, v13
	v_fma_f32 v6, v6, v33, v14
	v_fma_f32 v7, v7, v33, v15
	global_load_dwordx4 v[12:15], v2, s[38:39]
	global_load_dword v33, v3, s[42:43]
	s_add_u32 s38, s38, 0x10000
	s_addc_u32 s39, s39, 0
	s_add_u32 s42, s42, 0x200
	s_addc_u32 s43, s43, 0
	s_waitcnt vmcnt(15)
	global_store_dwordx4 v2, v[4:7], s[40:41]
	s_add_u32 s40, s40, 0x10000
	s_addc_u32 s41, s41, 0
	v_fma_f32 v4, v4, v34, v16
	v_fma_f32 v5, v5, v34, v17
	v_fma_f32 v6, v6, v34, v18
	v_fma_f32 v7, v7, v34, v19
	global_load_dwordx4 v[16:19], v2, s[38:39]
	global_load_dword v34, v3, s[42:43]
	s_add_u32 s38, s38, 0x10000
	s_addc_u32 s39, s39, 0
	s_add_u32 s42, s42, 0x200
	s_addc_u32 s43, s43, 0
	s_waitcnt vmcnt(15)
	global_store_dwordx4 v2, v[4:7], s[40:41]
	s_add_u32 s40, s40, 0x10000
	s_addc_u32 s41, s41, 0
	v_fma_f32 v4, v4, v35, v20
	v_fma_f32 v5, v5, v35, v21
	v_fma_f32 v6, v6, v35, v22
	v_fma_f32 v7, v7, v35, v23
	global_load_dwordx4 v[20:23], v2, s[38:39]
	global_load_dword v35, v3, s[42:43]
	s_add_u32 s38, s38, 0x10000
	s_addc_u32 s39, s39, 0
	s_add_u32 s42, s42, 0x200
	s_addc_u32 s43, s43, 0
	s_waitcnt vmcnt(15)
	global_store_dwordx4 v2, v[4:7], s[40:41]
	s_add_u32 s40, s40, 0x10000
	s_addc_u32 s41, s41, 0
	v_fma_f32 v4, v4, v36, v24
	v_fma_f32 v5, v5, v36, v25
	v_fma_f32 v6, v6, v36, v26
	v_fma_f32 v7, v7, v36, v27
	global_load_dwordx4 v[24:27], v2, s[38:39]
	global_load_dword v36, v3, s[42:43]
	s_add_u32 s38, s38, 0x10000
	s_addc_u32 s39, s39, 0
	s_add_u32 s42, s42, 0x200
	s_addc_u32 s43, s43, 0
	s_waitcnt vmcnt(15)
	global_store_dwordx4 v2, v[4:7], s[40:41]
	s_add_u32 s40, s40, 0x10000
	s_addc_u32 s41, s41, 0
	v_fma_f32 v4, v4, v37, v28
	v_fma_f32 v5, v5, v37, v29
	v_fma_f32 v6, v6, v37, v30
	v_fma_f32 v7, v7, v37, v31
	global_load_dwordx4 v[28:31], v2, s[38:39]
	global_load_dword v37, v3, s[42:43]
	s_add_u32 s38, s38, 0x10000
	s_addc_u32 s39, s39, 0
	s_add_u32 s42, s42, 0x200
	s_addc_u32 s43, s43, 0
	s_waitcnt vmcnt(15)
	global_store_dwordx4 v2, v[4:7], s[40:41]
	s_add_u32 s40, s40, 0x10000
	s_addc_u32 s41, s41, 0
	v_fma_f32 v4, v4, v32, v8
	v_fma_f32 v5, v5, v32, v9
	v_fma_f32 v6, v6, v32, v10
	v_fma_f32 v7, v7, v32, v11
	global_load_dwordx4 v[8:11], v2, s[38:39]
	global_load_dword v32, v3, s[42:43]
	s_add_u32 s38, s38, 0x10000
	s_addc_u32 s39, s39, 0
	s_add_u32 s42, s42, 0x200
	s_addc_u32 s43, s43, 0
	s_waitcnt vmcnt(15)
	global_store_dwordx4 v2, v[4:7], s[40:41]
	s_add_u32 s40, s40, 0x10000
	s_addc_u32 s41, s41, 0
	v_fma_f32 v4, v4, v33, v12
	v_fma_f32 v5, v5, v33, v13
	v_fma_f32 v6, v6, v33, v14
	v_fma_f32 v7, v7, v33, v15
	global_load_dwordx4 v[12:15], v2, s[38:39]
	global_load_dword v33, v3, s[42:43]
	s_add_u32 s38, s38, 0x10000
	s_addc_u32 s39, s39, 0
	s_add_u32 s42, s42, 0x200
	s_addc_u32 s43, s43, 0
	s_waitcnt vmcnt(15)
	global_store_dwordx4 v2, v[4:7], s[40:41]
	s_add_u32 s40, s40, 0x10000
	s_addc_u32 s41, s41, 0
	v_fma_f32 v4, v4, v34, v16
	v_fma_f32 v5, v5, v34, v17
	v_fma_f32 v6, v6, v34, v18
	v_fma_f32 v7, v7, v34, v19
	global_load_dwordx4 v[16:19], v2, s[38:39]
	global_load_dword v34, v3, s[42:43]
	s_add_u32 s38, s38, 0x10000
	s_addc_u32 s39, s39, 0
	s_add_u32 s42, s42, 0x200
	s_addc_u32 s43, s43, 0
	s_waitcnt vmcnt(15)
	global_store_dwordx4 v2, v[4:7], s[40:41]
	s_add_u32 s40, s40, 0x10000
	s_addc_u32 s41, s41, 0
	v_fma_f32 v4, v4, v35, v20
	v_fma_f32 v5, v5, v35, v21
	v_fma_f32 v6, v6, v35, v22
	v_fma_f32 v7, v7, v35, v23
	global_load_dwordx4 v[20:23], v2, s[38:39]
	global_load_dword v35, v3, s[42:43]
	s_add_u32 s38, s38, 0x10000
	s_addc_u32 s39, s39, 0
	s_add_u32 s42, s42, 0x200
	s_addc_u32 s43, s43, 0
	s_waitcnt vmcnt(15)
	global_store_dwordx4 v2, v[4:7], s[40:41]
	s_add_u32 s40, s40, 0x10000
	s_addc_u32 s41, s41, 0
	v_fma_f32 v4, v4, v36, v24
	v_fma_f32 v5, v5, v36, v25
	v_fma_f32 v6, v6, v36, v26
	v_fma_f32 v7, v7, v36, v27
	global_load_dwordx4 v[24:27], v2, s[38:39]
	global_load_dword v36, v3, s[42:43]
	s_add_u32 s38, s38, 0x10000
	s_addc_u32 s39, s39, 0
	s_add_u32 s42, s42, 0x200
	s_addc_u32 s43, s43, 0
	s_waitcnt vmcnt(15)
	global_store_dwordx4 v2, v[4:7], s[40:41]
	s_add_u32 s40, s40, 0x10000
	s_addc_u32 s41, s41, 0
	v_fma_f32 v4, v4, v37, v28
	v_fma_f32 v5, v5, v37, v29
	v_fma_f32 v6, v6, v37, v30
	v_fma_f32 v7, v7, v37, v31
	global_load_dwordx4 v[28:31], v2, s[38:39]
	global_load_dword v37, v3, s[42:43]
	s_add_u32 s38, s38, 0x10000
	s_addc_u32 s39, s39, 0
	s_add_u32 s42, s42, 0x200
	s_addc_u32 s43, s43, 0
	s_waitcnt vmcnt(15)
	global_store_dwordx4 v2, v[4:7], s[40:41]
	s_add_u32 s40, s40, 0x10000
	s_addc_u32 s41, s41, 0
	v_fma_f32 v4, v4, v32, v8
	v_fma_f32 v5, v5, v32, v9
	v_fma_f32 v6, v6, v32, v10
	v_fma_f32 v7, v7, v32, v11
	global_load_dwordx4 v[8:11], v2, s[38:39]
	global_load_dword v32, v3, s[42:43]
	s_add_u32 s38, s38, 0x10000
	s_addc_u32 s39, s39, 0
	s_add_u32 s42, s42, 0x200
	s_addc_u32 s43, s43, 0
	s_waitcnt vmcnt(15)
	global_store_dwordx4 v2, v[4:7], s[40:41]
	s_add_u32 s40, s40, 0x10000
	s_addc_u32 s41, s41, 0
	v_fma_f32 v4, v4, v33, v12
	v_fma_f32 v5, v5, v33, v13
	v_fma_f32 v6, v6, v33, v14
	v_fma_f32 v7, v7, v33, v15
	global_load_dwordx4 v[12:15], v2, s[38:39]
	global_load_dword v33, v3, s[42:43]
	s_add_u32 s38, s38, 0x10000
	s_addc_u32 s39, s39, 0
	s_add_u32 s42, s42, 0x200
	s_addc_u32 s43, s43, 0
	s_waitcnt vmcnt(15)
	global_store_dwordx4 v2, v[4:7], s[40:41]
	s_add_u32 s40, s40, 0x10000
	s_addc_u32 s41, s41, 0
	v_fma_f32 v4, v4, v34, v16
	v_fma_f32 v5, v5, v34, v17
	v_fma_f32 v6, v6, v34, v18
	v_fma_f32 v7, v7, v34, v19
	global_load_dwordx4 v[16:19], v2, s[38:39]
	global_load_dword v34, v3, s[42:43]
	s_add_u32 s38, s38, 0x10000
	s_addc_u32 s39, s39, 0
	s_add_u32 s42, s42, 0x200
	s_addc_u32 s43, s43, 0
	s_waitcnt vmcnt(15)
	global_store_dwordx4 v2, v[4:7], s[40:41]
	s_add_u32 s40, s40, 0x10000
	s_addc_u32 s41, s41, 0
	v_fma_f32 v4, v4, v35, v20
	v_fma_f32 v5, v5, v35, v21
	v_fma_f32 v6, v6, v35, v22
	v_fma_f32 v7, v7, v35, v23
	global_load_dwordx4 v[20:23], v2, s[38:39]
	global_load_dword v35, v3, s[42:43]
	s_add_u32 s38, s38, 0x10000
	s_addc_u32 s39, s39, 0
	s_add_u32 s42, s42, 0x200
	s_addc_u32 s43, s43, 0
	s_waitcnt vmcnt(15)
	global_store_dwordx4 v2, v[4:7], s[40:41]
	s_add_u32 s40, s40, 0x10000
	s_addc_u32 s41, s41, 0
	v_fma_f32 v4, v4, v36, v24
	v_fma_f32 v5, v5, v36, v25
	v_fma_f32 v6, v6, v36, v26
	v_fma_f32 v7, v7, v36, v27
	s_waitcnt vmcnt(13)
	global_store_dwordx4 v2, v[4:7], s[40:41]
	s_add_u32 s40, s40, 0x10000
	s_addc_u32 s41, s41, 0
	v_fma_f32 v4, v4, v37, v28
	v_fma_f32 v5, v5, v37, v29
	v_fma_f32 v6, v6, v37, v30
	v_fma_f32 v7, v7, v37, v31
	s_waitcnt vmcnt(11)
	global_store_dwordx4 v2, v[4:7], s[40:41]
	s_add_u32 s40, s40, 0x10000
	s_addc_u32 s41, s41, 0
	v_fma_f32 v4, v4, v32, v8
	v_fma_f32 v5, v5, v32, v9
	v_fma_f32 v6, v6, v32, v10
	v_fma_f32 v7, v7, v32, v11
	s_waitcnt vmcnt(9)
	global_store_dwordx4 v2, v[4:7], s[40:41]
	s_add_u32 s40, s40, 0x10000
	s_addc_u32 s41, s41, 0
	v_fma_f32 v4, v4, v33, v12
	v_fma_f32 v5, v5, v33, v13
	v_fma_f32 v6, v6, v33, v14
	v_fma_f32 v7, v7, v33, v15
	s_waitcnt vmcnt(7)
	global_store_dwordx4 v2, v[4:7], s[40:41]
	s_add_u32 s40, s40, 0x10000
	s_addc_u32 s41, s41, 0
	v_fma_f32 v4, v4, v34, v16
	v_fma_f32 v5, v5, v34, v17
	v_fma_f32 v6, v6, v34, v18
	v_fma_f32 v7, v7, v34, v19
	s_waitcnt vmcnt(5)
	global_store_dwordx4 v2, v[4:7], s[40:41]
	s_add_u32 s40, s40, 0x10000
	s_addc_u32 s41, s41, 0
